# PN: sum-of-squares wave reduction via DPP row ops + readlane (same pairwise tree) instead of 6 serialized ds_bpermute round trips
# speedup vs baseline: 1.0051x; 1.0051x over previous
; DI float wave_sum(float v) {
; #pragma unroll
;     for (int o = 1; o < 64; o <<= 1) v += __shfl_xor(v, o);
;     return v;
; DI void phase_norm(const Params& p, int l, const float* xin, LAS unsigned char* lds, int G, int bid) {
;     ...
;         for (int j = 0; j < 4; ++j) ss += (v[j].x * v[j].x + v[j].y * v[j].y) + (v[j].z * v[j].z + v[j].w * v[j].w);
;         const float rstd = 1.0f / sqrtf(wave_sum(ss) * (1.f / D) + EPS);
.LBB0_142:
	s_or_b64 exec, exec, s[0:1]
	v_ashrrev_i32_e32 v0, 31, v178
	v_lshrrev_b32_e32 v0, 19, v0
	v_add_u32_e32 v0, v178, v0
	v_pk_mul_f32 v[186:187], v[154:155], v[154:155]
	v_pk_mul_f32 v[188:189], v[156:157], v[156:157]
	v_pk_mul_f32 v[190:191], v[158:159], v[158:159]
	v_pk_mul_f32 v[192:193], v[160:161], v[160:161]
	v_ashrrev_i32_e32 v178, 13, v0
	v_mov_b32_e32 v194, v190
	v_mov_b32_e32 v195, v193
	v_pk_mov_b32 v[190:191], v[190:191], v[192:193] op_sel:[1,0]
	v_mov_b32_e32 v192, v186
	v_mov_b32_e32 v193, v189
	v_pk_mov_b32 v[186:187], v[186:187], v[188:189] op_sel:[1,0]
	v_mul_f32_e32 v0, v150, v150
	v_pk_add_f32 v[190:191], v[190:191], v[194:195]
	v_pk_add_f32 v[186:187], v[186:187], v[192:193]
	v_pk_fma_f32 v[188:189], v[150:151], v[150:151], v[0:1] op_sel_hi:[1,1,0]
	v_mul_f32_e32 v0, v152, v152
	v_pk_add_f32 v[190:191], v[190:191], v[190:191] op_sel_hi:[0,1]
	v_pk_add_f32 v[186:187], v[186:187], v[186:187] op_sel_hi:[0,1]
	v_pk_fma_f32 v[192:193], v[152:153], v[152:153], v[0:1] op_sel_hi:[1,1,0]
	v_mul_f32_e32 v188, v146, v146
	v_mul_f32_e32 v192, v147, v147
	v_mul_f32_e32 v190, v148, v148
	v_mul_f32_e32 v186, v149, v149
	v_pk_add_f32 v[188:189], v[188:189], v[192:193]
	v_pk_add_f32 v[186:187], v[190:191], v[186:187]
	s_mov_b32 s0, 0xf800000
	v_pk_add_f32 v[186:187], v[188:189], v[186:187]
	v_lshl_add_u32 v178, v178, 12, v185
	v_add_f32_e32 v0, v186, v187
	v_lshl_add_u64 v[194:195], s[92:93], 0, v[172:173]
	s_nop 1
	v_add_f32_dpp v0, v0, v0 quad_perm:[1,0,3,2] row_mask:0xf bank_mask:0xf
	s_nop 1
	v_add_f32_dpp v0, v0, v0 quad_perm:[2,3,0,1] row_mask:0xf bank_mask:0xf
	s_nop 1
	v_add_f32_dpp v0, v0, v0 row_half_mirror row_mask:0xf bank_mask:0xf
	s_nop 1
	v_add_f32_dpp v0, v0, v0 row_mirror row_mask:0xf bank_mask:0xf
	s_nop 3
	v_readlane_b32 s17, v0, 0
	v_readlane_b32 s23, v0, 16
	v_readlane_b32 s28, v0, 32
	v_readlane_b32 s29, v0, 48
	s_nop 1
	v_mov_b32_e32 v0, s17
	v_mov_b32_e32 v186, s28
	v_add_f32_e32 v0, s23, v0
	v_add_f32_e32 v186, s29, v186
	v_add_f32_e32 v0, v0, v186
	v_fmamk_f32 v0, v0, 0x3a800000, v204
	v_cmp_gt_f32_e32 vcc, s0, v0
	v_mul_f32_e32 v186, 0x4f800000, v0
	s_nop 0
	v_cndmask_b32_e32 v0, v0, v186, vcc
	v_sqrt_f32_e32 v186, v0
	s_nop 0
	v_add_u32_e32 v187, -1, v186
	v_fma_f32 v188, -v187, v186, v0
	v_cmp_ge_f32_e64 s[0:1], 0, v188
	v_add_u32_e32 v188, 1, v186
	s_nop 0
	v_cndmask_b32_e64 v187, v186, v187, s[0:1]
	v_fma_f32 v186, -v188, v186, v0
	v_cmp_lt_f32_e64 s[0:1], 0, v186
	s_nop 1
	v_cndmask_b32_e64 v186, v187, v188, s[0:1]
	v_mul_f32_e32 v187, 0x37800000, v186
	v_cndmask_b32_e32 v186, v186, v187, vcc
	v_cmp_class_f32_e32 vcc, v0, v205
	s_nop 1
	v_cndmask_b32_e32 v0, v186, v0, vcc
	v_div_scale_f32 v186, s[0:1], v0, v0, 1.0
	v_rcp_f32_e32 v187, v186
	s_brev_b32 s0, 32
	v_fma_f32 v188, -v186, v187, 1.0
	v_fmac_f32_e32 v187, v188, v187
	v_div_scale_f32 v188, vcc, 1.0, v0, 1.0
	v_mul_f32_e32 v189, v188, v187
	v_fma_f32 v190, -v186, v189, v188
	v_fmac_f32_e32 v189, v190, v187
	v_fma_f32 v186, -v186, v189, v188
	v_div_fmas_f32 v186, v186, v187, v189
	v_div_fixup_f32 v0, v186, v0, 1.0
	ds_read_b128 v[186:189], v178
	ds_read_b128 v[190:193], v178 offset:16384
	v_pk_mul_f32 v[158:159], v[158:159], v[0:1] op_sel_hi:[1,0]
	v_pk_mul_f32 v[160:161], v[160:161], v[0:1] op_sel_hi:[1,0]
	v_pk_mul_f32 v[154:155], v[154:155], v[0:1] op_sel_hi:[1,0]
	v_pk_mul_f32 v[156:157], v[156:157], v[0:1] op_sel_hi:[1,0]
	s_waitcnt lgkmcnt(0)
	v_pk_fma_f32 v[158:159], v[186:187], v[158:159], v[190:191]
	v_pk_fma_f32 v[160:161], v[188:189], v[160:161], v[192:193]
	v_pk_fma_f32 v[186:187], v[14:15], v[158:159], 0 op_sel_hi:[1,0,0]
	v_pk_fma_f32 v[188:189], v[16:17], v[158:159], 0 op_sel_hi:[1,0,0]
	v_pk_fma_f32 v[186:187], v[6:7], v[158:159], v[186:187] op_sel:[0,1,0]
	v_pk_fma_f32 v[190:191], v[10:11], v[158:159], 0 op_sel_hi:[1,0,0]
	v_pk_fma_f32 v[192:193], v[12:13], v[158:159], 0 op_sel_hi:[1,0,0]
	v_pk_fma_f32 v[186:187], v[30:31], v[160:161], v[186:187] op_sel_hi:[1,0,1]
	v_pk_fma_f32 v[188:189], v[8:9], v[158:159], v[188:189] op_sel:[0,1,0]
	v_pk_fma_f32 v[192:193], v[4:5], v[158:159], v[192:193] op_sel:[0,1,0]
	v_pk_fma_f32 v[190:191], v[2:3], v[158:159], v[190:191] op_sel:[0,1,0]
	v_pk_fma_f32 v[198:199], v[22:23], v[160:161], v[186:187] op_sel:[0,1,0]
	v_cvt_pk_bf16_f32 v186, v158, v159
	v_add_co_u32_e32 v158, vcc, s0, v194
	v_cvt_pk_bf16_f32 v187, v160, v161
	s_nop 0
	v_addc_co_u32_e32 v159, vcc, 0, v195, vcc
	v_pk_fma_f32 v[188:189], v[32:33], v[160:161], v[188:189] op_sel_hi:[1,0,1]
	v_pk_fma_f32 v[190:191], v[26:27], v[160:161], v[190:191] op_sel_hi:[1,0,1]
	v_pk_fma_f32 v[192:193], v[28:29], v[160:161], v[192:193] op_sel_hi:[1,0,1]
	global_store_dwordx2 v[158:159], v[186:187], off
	v_pk_fma_f32 v[196:197], v[24:25], v[160:161], v[188:189] op_sel:[0,1,0]
	v_pk_fma_f32 v[200:201], v[20:21], v[160:161], v[192:193] op_sel:[0,1,0]
	v_pk_fma_f32 v[218:219], v[18:19], v[160:161], v[190:191] op_sel:[0,1,0]
	ds_read_b128 v[186:189], v178 offset:1024
	ds_read_b128 v[190:193], v178 offset:17408
	v_pk_mul_f32 v[150:151], v[150:151], v[0:1] op_sel_hi:[1,0]
	v_pk_mul_f32 v[152:153], v[152:153], v[0:1] op_sel_hi:[1,0]
	v_pk_mul_f32 v[146:147], v[146:147], v[0:1] op_sel_hi:[1,0]
	v_pk_mul_f32 v[148:149], v[148:149], v[0:1] op_sel_hi:[1,0]
	s_waitcnt lgkmcnt(0)
	v_pk_fma_f32 v[154:155], v[186:187], v[154:155], v[190:191]
	v_pk_fma_f32 v[156:157], v[188:189], v[156:157], v[192:193]
	s_waitcnt vmcnt(9)
; #define LAS __attribute__((address_space(3)))
; DI void phase_norm(const Params& p, int l, const float* xin, LAS unsigned char* lds, int G, int bid) {
;     ...
; #pragma unroll
;         for (int j = 0; j < 4; ++j) {
;             const int k = 256 * j + 4 * lane;
;             const f32x4 aa = *(const LAS f32x4*)(pa + b * 1024 + k), sh = *(const LAS f32x4*)(pb + b * 1024 + k);
;             const f32x4 h = (v[j] * rstd) * aa + sh;
; #pragma unroll
;             for (int e = 0; e < 4; ++e) { g0 += w0[j][e] * h[e]; g1 += w1[j][e] * h[e]; }
;             o8[64 * j] = (unsigned long long)cvt_pk_bf16(h.x, h.y) | ((unsigned long long)cvt_pk_bf16(h.z, h.w) << 32);
;         }
; #pragma unroll
;         for (int e = 0; e < 4; ++e) { g0[e] = wave_sum(g0[e]); g1[e] = wave_sum(g1[e]); }
	v_pk_fma_f32 v[160:161], v[94:95], v[154:155], v[198:199] op_sel_hi:[1,0,1]
	v_pk_fma_f32 v[186:187], v[96:97], v[154:155], v[196:197] op_sel_hi:[1,0,1]
	v_pk_fma_f32 v[188:189], v[90:91], v[154:155], v[218:219] op_sel_hi:[1,0,1]
	v_pk_fma_f32 v[190:191], v[92:93], v[154:155], v[200:201] op_sel_hi:[1,0,1]
	v_pk_fma_f32 v[186:187], v[88:89], v[154:155], v[186:187] op_sel:[0,1,0]
	v_pk_fma_f32 v[160:161], v[86:87], v[154:155], v[160:161] op_sel:[0,1,0]
	v_pk_fma_f32 v[190:191], v[84:85], v[154:155], v[190:191] op_sel:[0,1,0]
	v_pk_fma_f32 v[188:189], v[82:83], v[154:155], v[188:189] op_sel:[0,1,0]
	v_cvt_pk_bf16_f32 v154, v154, v155
	v_cvt_pk_bf16_f32 v155, v156, v157
	v_pk_fma_f32 v[160:161], v[34:35], v[156:157], v[160:161] op_sel_hi:[1,0,1]
	v_pk_fma_f32 v[186:187], v[36:37], v[156:157], v[186:187] op_sel_hi:[1,0,1]
	v_pk_fma_f32 v[188:189], v[46:47], v[156:157], v[188:189] op_sel_hi:[1,0,1]
	v_pk_fma_f32 v[190:191], v[48:49], v[156:157], v[190:191] op_sel_hi:[1,0,1]
	global_store_dwordx2 v[158:159], v[154:155], off offset:512
	v_pk_fma_f32 v[192:193], v[44:45], v[156:157], v[186:187] op_sel:[0,1,0]
	v_pk_fma_f32 v[160:161], v[42:43], v[156:157], v[160:161] op_sel:[0,1,0]
	v_pk_fma_f32 v[190:191], v[40:41], v[156:157], v[190:191] op_sel:[0,1,0]
	v_pk_fma_f32 v[194:195], v[38:39], v[156:157], v[188:189] op_sel:[0,1,0]
	ds_read_b128 v[154:157], v178 offset:2048
	ds_read_b128 v[186:189], v178 offset:18432
	s_waitcnt lgkmcnt(0)
	v_pk_fma_f32 v[150:151], v[154:155], v[150:151], v[186:187]
	v_pk_fma_f32 v[152:153], v[156:157], v[152:153], v[188:189]
	s_waitcnt vmcnt(6)
	v_pk_fma_f32 v[154:155], v[110:111], v[150:151], v[160:161] op_sel_hi:[1,0,1]
	v_pk_fma_f32 v[156:157], v[112:113], v[150:151], v[192:193] op_sel_hi:[1,0,1]
	v_pk_fma_f32 v[160:161], v[106:107], v[150:151], v[194:195] op_sel_hi:[1,0,1]
	v_pk_fma_f32 v[186:187], v[108:109], v[150:151], v[190:191] op_sel_hi:[1,0,1]
	v_pk_fma_f32 v[156:157], v[104:105], v[150:151], v[156:157] op_sel:[0,1,0]
	v_pk_fma_f32 v[154:155], v[102:103], v[150:151], v[154:155] op_sel:[0,1,0]
	v_pk_fma_f32 v[186:187], v[100:101], v[150:151], v[186:187] op_sel:[0,1,0]
	v_pk_fma_f32 v[160:161], v[98:99], v[150:151], v[160:161] op_sel:[0,1,0]
	v_cvt_pk_bf16_f32 v150, v150, v151
	v_cvt_pk_bf16_f32 v151, v152, v153
	v_pk_fma_f32 v[154:155], v[50:51], v[152:153], v[154:155] op_sel_hi:[1,0,1]
	v_pk_fma_f32 v[156:157], v[52:53], v[152:153], v[156:157] op_sel_hi:[1,0,1]
	v_pk_fma_f32 v[160:161], v[62:63], v[152:153], v[160:161] op_sel_hi:[1,0,1]
	v_pk_fma_f32 v[186:187], v[64:65], v[152:153], v[186:187] op_sel_hi:[1,0,1]
	global_store_dwordx2 v[158:159], v[150:151], off offset:1024
	v_pk_fma_f32 v[188:189], v[60:61], v[152:153], v[156:157] op_sel:[0,1,0]
	v_pk_fma_f32 v[190:191], v[58:59], v[152:153], v[154:155] op_sel:[0,1,0]
	v_pk_fma_f32 v[186:187], v[56:57], v[152:153], v[186:187] op_sel:[0,1,0]
	v_pk_fma_f32 v[160:161], v[54:55], v[152:153], v[160:161] op_sel:[0,1,0]
	ds_read_b128 v[150:153], v178 offset:3072
	ds_read_b128 v[154:157], v178 offset:19456
	s_waitcnt lgkmcnt(0)
	v_pk_fma_f32 v[146:147], v[146:147], v[150:151], v[154:155]
	s_waitcnt vmcnt(3)
	v_pk_fma_f32 v[150:151], v[126:127], v[146:147], v[190:191] op_sel_hi:[1,0,1]
	v_pk_fma_f32 v[148:149], v[148:149], v[152:153], v[156:157]
	v_pk_fma_f32 v[150:151], v[118:119], v[146:147], v[150:151] op_sel:[0,1,0]
	v_pk_fma_f32 v[152:153], v[128:129], v[146:147], v[188:189] op_sel_hi:[1,0,1]
	v_pk_fma_f32 v[154:155], v[122:123], v[146:147], v[160:161] op_sel_hi:[1,0,1]
	v_pk_fma_f32 v[156:157], v[124:125], v[146:147], v[186:187] op_sel_hi:[1,0,1]
	v_pk_fma_f32 v[150:151], v[66:67], v[148:149], v[150:151] op_sel_hi:[1,0,1]
	v_pk_fma_f32 v[152:153], v[120:121], v[146:147], v[152:153] op_sel:[0,1,0]
	v_pk_fma_f32 v[156:157], v[116:117], v[146:147], v[156:157] op_sel:[0,1,0]
	v_pk_fma_f32 v[154:155], v[114:115], v[146:147], v[154:155] op_sel:[0,1,0]
	v_pk_fma_f32 v[160:161], v[74:75], v[148:149], v[150:151] op_sel:[0,1,0]
	v_cvt_pk_bf16_f32 v146, v146, v147
	v_cvt_pk_bf16_f32 v147, v148, v149
	global_store_dwordx2 v[158:159], v[146:147], off offset:1536
	ds_bpermute_b32 v146, v163, v160
	ds_bpermute_b32 v147, v163, v161
	v_pk_fma_f32 v[152:153], v[68:69], v[148:149], v[152:153] op_sel_hi:[1,0,1]
	v_pk_fma_f32 v[154:155], v[78:79], v[148:149], v[154:155] op_sel_hi:[1,0,1]
	v_pk_fma_f32 v[156:157], v[80:81], v[148:149], v[156:157] op_sel_hi:[1,0,1]
	v_pk_fma_f32 v[152:153], v[76:77], v[148:149], v[152:153] op_sel:[0,1,0]
	v_pk_fma_f32 v[150:151], v[72:73], v[148:149], v[156:157] op_sel:[0,1,0]
	v_pk_fma_f32 v[154:155], v[70:71], v[148:149], v[154:155] op_sel:[0,1,0]
	ds_bpermute_b32 v156, v163, v154
	s_waitcnt lgkmcnt(1)
; DI void phase_norm(const Params& p, int l, const float* xin, LAS unsigned char* lds, int G, int bid) {
;     ...
; #pragma unroll
;         for (int e = 0; e < 4; ++e) { g0[e] = wave_sum(g0[e]); g1[e] = wave_sum(g1[e]); }
;         if (lane == 0) { *(f32x4*)(gates + (size_t)row * 8) = g0; *(f32x4*)(gates + (size_t)row * 8 + 4) = g1; }
	v_pk_add_f32 v[146:147], v[160:161], v[146:147]
	ds_bpermute_b32 v157, v163, v155
	ds_bpermute_b32 v158, v163, v152
	ds_bpermute_b32 v160, v163, v150
	ds_bpermute_b32 v159, v163, v153
	ds_bpermute_b32 v161, v163, v151
	s_waitcnt lgkmcnt(4)
	v_pk_add_f32 v[154:155], v[154:155], v[156:157]
	ds_bpermute_b32 v148, v180, v146
	ds_bpermute_b32 v149, v180, v147
	s_waitcnt lgkmcnt(3)
	v_pk_add_f32 v[152:153], v[152:153], v[158:159]
	s_waitcnt lgkmcnt(2)
	v_pk_add_f32 v[150:151], v[150:151], v[160:161]
	ds_bpermute_b32 v156, v180, v154
	ds_bpermute_b32 v157, v180, v155
	ds_bpermute_b32 v158, v180, v152
	ds_bpermute_b32 v159, v180, v153
	ds_bpermute_b32 v160, v180, v150
	ds_bpermute_b32 v161, v180, v151
	s_waitcnt lgkmcnt(6)
	v_pk_add_f32 v[146:147], v[146:147], v[148:149]
	s_waitcnt lgkmcnt(4)
	v_pk_add_f32 v[154:155], v[154:155], v[156:157]
	s_waitcnt lgkmcnt(2)
	v_pk_add_f32 v[152:153], v[152:153], v[158:159]
	ds_bpermute_b32 v148, v181, v146
	s_waitcnt lgkmcnt(1)
	v_pk_add_f32 v[150:151], v[150:151], v[160:161]
	ds_bpermute_b32 v149, v181, v147
	ds_bpermute_b32 v156, v181, v154
	ds_bpermute_b32 v157, v181, v155
	ds_bpermute_b32 v158, v181, v152
	ds_bpermute_b32 v159, v181, v153
	ds_bpermute_b32 v160, v181, v150
	ds_bpermute_b32 v161, v181, v151
	s_waitcnt lgkmcnt(6)
	v_pk_add_f32 v[146:147], v[146:147], v[148:149]
	s_waitcnt lgkmcnt(4)
	v_pk_add_f32 v[154:155], v[154:155], v[156:157]
	s_waitcnt lgkmcnt(2)
	v_pk_add_f32 v[152:153], v[152:153], v[158:159]
	ds_bpermute_b32 v148, v182, v146
	s_waitcnt lgkmcnt(1)
	v_pk_add_f32 v[150:151], v[150:151], v[160:161]
	ds_bpermute_b32 v149, v182, v147
	ds_bpermute_b32 v156, v182, v154
	ds_bpermute_b32 v157, v182, v155
	ds_bpermute_b32 v158, v182, v152
	ds_bpermute_b32 v159, v182, v153
	ds_bpermute_b32 v160, v182, v150
	ds_bpermute_b32 v161, v182, v151
	s_waitcnt lgkmcnt(6)
	v_pk_add_f32 v[146:147], v[146:147], v[148:149]
	s_waitcnt lgkmcnt(4)
	v_pk_add_f32 v[154:155], v[154:155], v[156:157]
	s_waitcnt lgkmcnt(2)
	v_pk_add_f32 v[152:153], v[152:153], v[158:159]
	ds_bpermute_b32 v148, v183, v146
	s_waitcnt lgkmcnt(1)
	v_pk_add_f32 v[150:151], v[150:151], v[160:161]
	ds_bpermute_b32 v149, v183, v147
	ds_bpermute_b32 v156, v183, v154
	ds_bpermute_b32 v157, v183, v155
	ds_bpermute_b32 v158, v183, v152
	ds_bpermute_b32 v159, v183, v153
	ds_bpermute_b32 v160, v183, v150
	ds_bpermute_b32 v161, v183, v151
	s_waitcnt lgkmcnt(6)
	v_pk_add_f32 v[146:147], v[146:147], v[148:149]
	s_waitcnt lgkmcnt(4)
	v_pk_add_f32 v[154:155], v[154:155], v[156:157]
	s_waitcnt lgkmcnt(2)
	v_pk_add_f32 v[152:153], v[152:153], v[158:159]
	ds_bpermute_b32 v148, v184, v146
	s_waitcnt lgkmcnt(1)
	v_pk_add_f32 v[150:151], v[150:151], v[160:161]
	ds_bpermute_b32 v149, v184, v147
	ds_bpermute_b32 v156, v184, v154
	ds_bpermute_b32 v157, v184, v155
	ds_bpermute_b32 v158, v184, v152
	ds_bpermute_b32 v159, v184, v153
	ds_bpermute_b32 v160, v184, v150
	ds_bpermute_b32 v161, v184, v151
	s_and_saveexec_b64 s[0:1], s[40:41]
	s_cbranch_execz .LBB0_139
	s_waitcnt lgkmcnt(6)
	v_pk_add_f32 v[148:149], v[146:147], v[148:149]
	v_lshl_add_u64 v[146:147], s[92:93], 0, v[176:177]
	v_add_co_u32_e32 v146, vcc, 0x200000, v146
	s_waitcnt lgkmcnt(0)
	v_pk_add_f32 v[188:189], v[150:151], v[160:161]
	v_pk_add_f32 v[150:151], v[152:153], v[158:159]
	v_addc_co_u32_e32 v147, vcc, 0, v147, vcc
	v_pk_add_f32 v[186:187], v[154:155], v[156:157]
	global_store_dwordx4 v[146:147], v[148:151], off
	global_store_dwordx4 v[146:147], v[186:189], off offset:16
	s_branch .LBB0_139
